# rstd table prologue loop split across both wave halves (half the serialized round trips) in 5 GEMM phases
# baseline (speedup 1.0000x reference)
.LBB0_302:
	s_cmp_lt_i32 s94, 2
	s_cselect_b64 s[0:1], -1, 0
	s_and_b64 s[2:3], s[0:1], s[2:3]
	s_andn2_b64 vcc, exec, s[2:3]
	s_mov_b32 s2, s90
	v_writelane_b32 v253, s2, 56
	s_nop 1
	v_writelane_b32 v253, s3, 57
	v_writelane_b32 v253, s97, 58
	s_cbranch_vccnz .LBB0_321
	v_readlane_b32 s4, v253, 0
	s_mov_b64 s[2:3], s[92:93]
	v_readlane_b32 s5, v253, 1
	s_load_dword s62, s[4:5], 0xf0
	v_and_b32_e32 v0, 0xff, v176
	v_lshlrev_b32_e32 v0, 6, v0
	v_mov_b32_e32 v1, 0
	s_mov_b64 s[4:5], 0x1f400000
	v_lshlrev_b32_e32 v12, 2, v176
	s_waitcnt lgkmcnt(0)
	v_cvt_f32_u32_e32 v2, s62
	s_movk_i32 s6, 0x100
	v_readfirstlane_b32 s33, v176
	v_cmp_gt_u32_e64 s[8:9], s6, v176
	v_rcp_iflag_f32_e32 v2, v2
	s_movk_i32 s12, 0x161
	v_mov_b32_e32 v6, 0x358637bd
	s_mov_b32 s13, 0x800000
	v_mul_f32_e32 v2, 0x4f7ffffe, v2
	v_cvt_u32_f32_e32 v4, v2
	v_lshl_add_u64 v[2:3], s[2:3], 0, v[0:1]
	v_lshl_add_u64 v[2:3], v[2:3], 0, s[4:5]
	s_sub_i32 s4, 0, s62
	v_readfirstlane_b32 s5, v4
	s_mul_i32 s4, s4, s5
	s_mul_hi_u32 s4, s5, s4
	s_add_i32 s5, s5, s4
	s_mul_hi_u32 s4, s90, s5
	s_mul_i32 s4, s4, s62
	s_sub_i32 s4, s90, s4
	s_sub_i32 s5, s4, s62
	s_cmp_ge_u32 s4, s62
	s_cselect_b32 s4, s5, s4
	s_sub_i32 s5, s4, s62
	s_cmp_ge_u32 s4, s62
	s_cselect_b32 s4, s5, s4
	s_ashr_i32 s5, s4, 31
	s_ashr_i32 s63, s62, 31
	v_add_u32_e32 v1, 0x20400, v12
	v_mov_b64_e32 v[4:5], 0xaff
	s_mov_b64 s[6:7], s[4:5]
	v_readfirstlane_b32 s10, v176
	s_nop 0
	s_cmpk_lt_u32 s10, 0x100
	s_cbranch_scc1 .Lrstd_skip_1
	s_add_u32 s6, s6, s62
	s_addc_u32 s7, s7, s63

.LBB0_304:
	s_or_b64 exec, exec, s[10:11]
	s_add_u32 s6, s6, s62
	s_addc_u32 s7, s7, s63
	s_add_u32 s6, s6, s62
	v_add_u32_e32 v1, 0x800, v1
	s_addc_u32 s7, s7, s63
	s_mov_b64 s[10:11], 0

.LBB0_306:
	v_cmp_gt_i64_e32 vcc, s[6:7], v[4:5]
	s_mov_b64 s[10:11], -1
	s_cbranch_vccnz .LBB0_305
	s_mov_b64 s[10:11], exec
	s_cbranch_execz .LBB0_304
	s_ashr_i32 s14, s6, 31
	s_lshr_b32 s14, s14, 29
	s_add_i32 s14, s6, s14
	s_ashr_i32 s15, s14, 3
	s_and_b32 s14, s14, -8
	s_sub_i32 s14, s6, s14
	s_cmp_lt_i32 s14, 0
	s_cselect_b32 s16, s12, 0x160
	s_mul_i32 s14, s16, s14
	s_add_i32 s14, s14, s15
	s_mul_hi_i32 s15, s14, 0x2e8ba2e9
	s_lshr_b32 s16, s15, 31
	s_ashr_i32 s15, s15, 5
	s_add_i32 s15, s15, s16
	s_lshl_b32 s16, s15, 3
	s_sub_i32 s17, 0x80, s16
	s_min_i32 s17, s17, 8
	s_abs_i32 s17, s17
	v_cvt_f32_u32_e32 v7, s17
	s_sub_i32 s18, 0, s17
	s_mulk_i32 s15, 0xb0
	s_sub_i32 s14, s14, s15
	v_rcp_iflag_f32_e32 v7, v7
	s_ashr_i32 s15, s14, 31
	s_abs_i32 s14, s14
	v_mul_f32_e32 v7, 0x4f7ffffe, v7
	v_cvt_u32_f32_e32 v7, v7
	s_nop 0
	v_readfirstlane_b32 s19, v7
	s_mul_i32 s18, s18, s19
	s_mul_hi_u32 s18, s19, s18
	s_add_i32 s19, s19, s18
	s_mul_hi_u32 s18, s14, s19
	s_mul_i32 s18, s18, s17
	s_sub_i32 s14, s14, s18
	s_sub_i32 s18, s14, s17
	s_cmp_ge_u32 s14, s17
	s_cselect_b32 s14, s18, s14
	s_sub_i32 s18, s14, s17
	s_cmp_ge_u32 s14, s17
	s_cselect_b32 s14, s18, s14
	s_xor_b32 s14, s14, s15
	s_sub_i32 s14, s14, s15
	s_add_i32 s14, s14, s16
	s_ashr_i32 s15, s14, 31
	s_lshl_b64 s[14:15], s[14:15], 14
	v_lshl_add_u64 v[22:23], v[2:3], 0, s[14:15]
	flat_load_dwordx4 v[8:11], v[22:23]
	flat_load_dwordx4 v[14:17], v[22:23] offset:16
	flat_load_dwordx4 v[18:21], v[22:23] offset:32
	s_nop 0
	flat_load_dwordx4 v[22:25], v[22:23] offset:48
	s_waitcnt vmcnt(0) lgkmcnt(0)
	v_mov_b32_e32 v26, v9
	v_mov_b32_e32 v27, v10
	v_mov_b32_e32 v28, v15
	v_mov_b32_e32 v29, v16
	v_mov_b32_e32 v9, v11
	v_mov_b32_e32 v15, v17
	v_mov_b32_e32 v10, v19
	v_mov_b32_e32 v16, v21
	v_pk_add_f32 v[8:9], v[26:27], v[8:9]
	v_pk_add_f32 v[14:15], v[28:29], v[14:15]
	v_pk_add_f32 v[10:11], v[18:19], v[10:11]
	v_pk_add_f32 v[16:17], v[20:21], v[16:17]
	v_pk_add_f32 v[8:9], v[8:9], v[8:9] op_sel:[0,1] op_sel_hi:[1,0]
	v_pk_add_f32 v[14:15], v[14:15], v[14:15] op_sel:[0,1] op_sel_hi:[1,0]
	v_mov_b32_e32 v11, v24
	v_mov_b32_e32 v17, v25
	v_mov_b32_e32 v9, v22
	v_mov_b32_e32 v15, v23
	v_pk_add_f32 v[10:11], v[10:11], v[16:17]
	v_pk_add_f32 v[8:9], v[8:9], v[14:15]
	s_nop 0
	v_pk_add_f32 v[8:9], v[8:9], v[10:11]
	s_nop 0
	v_add_f32_e32 v7, v8, v9
	v_fmamk_f32 v7, v7, 0x3a800000, v6
	v_mul_f32_e32 v8, 0x4b800000, v7
	v_cmp_gt_f32_e32 vcc, s13, v7
	s_nop 1
	v_cndmask_b32_e32 v7, v7, v8, vcc
	v_rsq_f32_e32 v7, v7
	s_nop 0
	v_mul_f32_e32 v8, 0x45800000, v7
	v_cndmask_b32_e32 v7, v7, v8, vcc
	ds_write_b32 v1, v7
	s_branch .LBB0_304

.LBB0_511:
	s_cmp_lt_i32 s94, 4
	s_cselect_b64 s[0:1], -1, 0
	s_and_b64 s[2:3], s[0:1], s[2:3]
	s_andn2_b64 vcc, exec, s[2:3]
	s_cbranch_vccnz .LBB0_544
	v_readlane_b32 s4, v253, 0
	s_mov_b64 s[2:3], s[92:93]
	v_readlane_b32 s5, v253, 1
	s_load_dword s13, s[4:5], 0xf0
	v_and_b32_e32 v0, 0xff, v176
	v_lshlrev_b32_e32 v0, 6, v0
	v_mov_b32_e32 v1, 0
	s_mov_b64 s[4:5], 0x1f400000
	v_lshlrev_b32_e32 v10, 2, v176
	s_waitcnt lgkmcnt(0)
	v_cvt_f32_u32_e32 v2, s13
	s_movk_i32 s6, 0x100
	v_readfirstlane_b32 s40, v176
	v_cmp_gt_u32_e64 s[8:9], s6, v176
	v_rcp_iflag_f32_e32 v2, v2
	s_movk_i32 s12, 0xe1
	v_mov_b32_e32 v6, 0x358637bd
	s_mov_b32 s14, 0x800000
	v_mul_f32_e32 v2, 0x4f7ffffe, v2
	v_cvt_u32_f32_e32 v4, v2
	v_lshl_add_u64 v[2:3], s[2:3], 0, v[0:1]
	v_lshl_add_u64 v[2:3], v[2:3], 0, s[4:5]
	s_sub_i32 s4, 0, s13
	v_readfirstlane_b32 s5, v4
	s_mul_i32 s4, s4, s5
	s_mul_hi_u32 s4, s5, s4
	s_add_i32 s5, s5, s4
	s_mul_hi_u32 s4, s90, s5
	s_mul_i32 s4, s4, s13
	s_sub_i32 s4, s90, s4
	s_sub_i32 s5, s4, s13
	s_cmp_ge_u32 s4, s13
	s_cselect_b32 s4, s5, s4
	s_sub_i32 s5, s4, s13
	s_cmp_ge_u32 s4, s13
	s_cselect_b32 s4, s5, s4
	s_ashr_i32 s5, s4, 31
	s_ashr_i32 s60, s13, 31
	v_add_u32_e32 v1, 0x20400, v10
	v_mov_b64_e32 v[4:5], 0x6ff
	s_mov_b64 s[6:7], s[4:5]
	v_readfirstlane_b32 s10, v176
	s_nop 0
	s_cmpk_lt_u32 s10, 0x100
	s_cbranch_scc1 .Lrstd_skip_2
	s_add_u32 s6, s6, s13
	s_addc_u32 s7, s7, s60

.LBB0_513:
	s_or_b64 exec, exec, s[10:11]
	s_add_u32 s6, s6, s13
	s_addc_u32 s7, s7, s60
	s_add_u32 s6, s6, s13
	v_add_u32_e32 v1, 0x800, v1
	s_addc_u32 s7, s7, s60
	s_mov_b64 s[10:11], 0

.LBB0_515:
	v_cmp_gt_i64_e32 vcc, s[6:7], v[4:5]
	s_mov_b64 s[10:11], -1
	s_cbranch_vccnz .LBB0_514
	s_mov_b64 s[10:11], exec
	s_cbranch_execz .LBB0_513
	s_ashr_i32 s15, s6, 31
	s_lshr_b32 s15, s15, 29
	s_add_i32 s15, s6, s15
	s_ashr_i32 s16, s15, 3
	s_and_b32 s15, s15, -8
	s_sub_i32 s15, s6, s15
	s_cmp_lt_i32 s15, 0
	s_cselect_b32 s17, s12, 0xe0
	s_mul_i32 s15, s17, s15
	s_add_i32 s15, s15, s16
	s_mul_hi_i32 s16, s15, 0x92492493
	s_add_i32 s16, s16, s15
	s_lshr_b32 s17, s16, 31
	s_ashr_i32 s16, s16, 6
	s_add_i32 s16, s16, s17
	s_lshl_b32 s17, s16, 3
	s_sub_i32 s18, 0x80, s17
	s_min_i32 s18, s18, 8
	s_abs_i32 s18, s18
	v_cvt_f32_u32_e32 v7, s18
	s_sub_i32 s19, 0, s18
	s_mulk_i32 s16, 0x70
	s_sub_i32 s15, s15, s16
	v_rcp_iflag_f32_e32 v7, v7
	s_ashr_i32 s16, s15, 31
	s_abs_i32 s15, s15
	v_mul_f32_e32 v7, 0x4f7ffffe, v7
	v_cvt_u32_f32_e32 v7, v7
	s_nop 0
	v_readfirstlane_b32 s20, v7
	s_mul_i32 s19, s19, s20
	s_mul_hi_u32 s19, s20, s19
	s_add_i32 s20, s20, s19
	s_mul_hi_u32 s19, s15, s20
	s_mul_i32 s19, s19, s18
	s_sub_i32 s15, s15, s19
	s_sub_i32 s19, s15, s18
	s_cmp_ge_u32 s15, s18
	s_cselect_b32 s15, s19, s15
	s_sub_i32 s19, s15, s18
	s_cmp_ge_u32 s15, s18
	s_cselect_b32 s15, s19, s15
	s_xor_b32 s15, s15, s16
	s_sub_i32 s15, s15, s16
	s_add_i32 s16, s15, s17
	s_ashr_i32 s17, s16, 31
	s_lshl_b64 s[16:17], s[16:17], 14
	v_lshl_add_u64 v[8:9], v[2:3], 0, s[16:17]
	s_waitcnt vmcnt(0)
	flat_load_dwordx4 v[12:15], v[8:9]
	flat_load_dwordx4 v[16:19], v[8:9] offset:16
	flat_load_dwordx4 v[20:23], v[8:9] offset:32
	flat_load_dwordx4 v[24:27], v[8:9] offset:48
	s_waitcnt vmcnt(0) lgkmcnt(0)
	v_mov_b32_e32 v8, v13
	v_mov_b32_e32 v9, v14
	v_mov_b32_e32 v28, v17
	v_mov_b32_e32 v29, v18
	v_mov_b32_e32 v13, v15
	v_mov_b32_e32 v17, v19
	v_mov_b32_e32 v14, v21
	v_mov_b32_e32 v18, v23
	v_pk_add_f32 v[8:9], v[8:9], v[12:13]
	v_pk_add_f32 v[12:13], v[28:29], v[16:17]
	v_pk_add_f32 v[14:15], v[20:21], v[14:15]
	v_pk_add_f32 v[16:17], v[22:23], v[18:19]
	v_pk_add_f32 v[8:9], v[8:9], v[8:9] op_sel:[0,1] op_sel_hi:[1,0]
	v_pk_add_f32 v[12:13], v[12:13], v[12:13] op_sel:[0,1] op_sel_hi:[1,0]
	v_mov_b32_e32 v15, v26
	v_mov_b32_e32 v17, v27
	v_mov_b32_e32 v9, v24
	v_mov_b32_e32 v13, v25
	v_pk_add_f32 v[14:15], v[14:15], v[16:17]
	v_pk_add_f32 v[8:9], v[8:9], v[12:13]
	s_nop 0
	v_pk_add_f32 v[8:9], v[8:9], v[14:15]
	s_nop 0
	v_add_f32_e32 v7, v8, v9
	v_fmamk_f32 v7, v7, 0x3a800000, v6
	v_mul_f32_e32 v8, 0x4b800000, v7
	v_cmp_gt_f32_e32 vcc, s14, v7
	s_nop 1
	v_cndmask_b32_e32 v7, v7, v8, vcc
	v_rsq_f32_e32 v7, v7
	s_nop 0
	v_mul_f32_e32 v8, 0x45800000, v7
	v_cndmask_b32_e32 v7, v7, v8, vcc
	ds_write_b32 v1, v7
	s_branch .LBB0_513

.LBB0_1550:
	s_cmp_lt_i32 s94, 9
	s_cselect_b64 s[0:1], -1, 0
	s_and_b64 s[2:3], s[0:1], s[2:3]
	s_andn2_b64 vcc, exec, s[2:3]
	s_cbranch_vccnz .LBB0_1569
	v_readlane_b32 s2, v253, 0
	s_mov_b64 s[8:9], s[92:93]
	v_readlane_b32 s3, v253, 1
	s_load_dword s29, s[2:3], 0xf0
	v_and_b32_e32 v0, 0xff, v176
	v_lshlrev_b32_e32 v0, 6, v0
	s_waitcnt lgkmcnt(0)
	v_mov_b32_e32 v1, 0
	s_mov_b64 s[2:3], 0x1f400000
	v_lshlrev_b32_e32 v12, 2, v176
	v_cvt_f32_u32_e32 v2, s29
	s_movk_i32 s4, 0x100
	v_readfirstlane_b32 s28, v176
	v_cmp_gt_u32_e64 s[6:7], s4, v176
	v_rcp_iflag_f32_e32 v2, v2
	s_movk_i32 s12, 0x161
	v_mov_b32_e32 v6, 0x358637bd
	s_mov_b32 s13, 0x800000
	v_mul_f32_e32 v2, 0x4f7ffffe, v2
	v_cvt_u32_f32_e32 v4, v2
	v_lshl_add_u64 v[2:3], s[8:9], 0, v[0:1]
	v_lshl_add_u64 v[2:3], v[2:3], 0, s[2:3]
	s_sub_i32 s2, 0, s29
	v_readfirstlane_b32 s3, v4
	s_mul_i32 s2, s2, s3
	s_mul_hi_u32 s2, s3, s2
	s_add_i32 s3, s3, s2
	s_mul_hi_u32 s2, s90, s3
	s_mul_i32 s2, s2, s29
	s_sub_i32 s2, s90, s2
	s_sub_i32 s3, s2, s29
	s_cmp_ge_u32 s2, s29
	s_cselect_b32 s2, s3, s2
	s_sub_i32 s3, s2, s29
	s_cmp_ge_u32 s2, s29
	s_cselect_b32 s2, s3, s2
	s_ashr_i32 s3, s2, 31
	s_ashr_i32 s30, s29, 31
	v_add_u32_e32 v1, 0x20400, v12
	v_mov_b64_e32 v[4:5], 0xaff
	s_mov_b64 s[4:5], s[2:3]
	v_readfirstlane_b32 s10, v176
	s_nop 0
	s_cmpk_lt_u32 s10, 0x100
	s_cbranch_scc1 .Lrstd_skip_3
	s_add_u32 s4, s4, s29
	s_addc_u32 s5, s5, s30

.LBB0_1552:
	s_or_b64 exec, exec, s[10:11]
	s_add_u32 s4, s4, s29
	s_addc_u32 s5, s5, s30
	s_add_u32 s4, s4, s29
	v_add_u32_e32 v1, 0x800, v1
	s_addc_u32 s5, s5, s30
	s_mov_b64 s[10:11], 0

.LBB0_1554:
	v_cmp_gt_i64_e32 vcc, s[4:5], v[4:5]
	s_mov_b64 s[10:11], -1
	s_cbranch_vccnz .LBB0_1553
	s_mov_b64 s[10:11], exec
	s_cbranch_execz .LBB0_1552
	s_ashr_i32 s14, s4, 31
	s_lshr_b32 s14, s14, 29
	s_add_i32 s14, s4, s14
	s_ashr_i32 s15, s14, 3
	s_and_b32 s14, s14, -8
	s_sub_i32 s14, s4, s14
	s_cmp_lt_i32 s14, 0
	s_cselect_b32 s16, s12, 0x160
	s_mul_i32 s14, s16, s14
	s_add_i32 s14, s14, s15
	s_mul_hi_i32 s15, s14, 0x2e8ba2e9
	s_lshr_b32 s16, s15, 31
	s_ashr_i32 s15, s15, 5
	s_add_i32 s15, s15, s16
	s_lshl_b32 s16, s15, 3
	s_sub_i32 s17, 0x80, s16
	s_min_i32 s17, s17, 8
	s_abs_i32 s17, s17
	v_cvt_f32_u32_e32 v7, s17
	s_sub_i32 s18, 0, s17
	s_mulk_i32 s15, 0xb0
	s_sub_i32 s14, s14, s15
	v_rcp_iflag_f32_e32 v7, v7
	s_ashr_i32 s15, s14, 31
	s_abs_i32 s14, s14
	v_mul_f32_e32 v7, 0x4f7ffffe, v7
	v_cvt_u32_f32_e32 v7, v7
	s_nop 0
	v_readfirstlane_b32 s19, v7
	s_mul_i32 s18, s18, s19
	s_mul_hi_u32 s18, s19, s18
	s_add_i32 s19, s19, s18
	s_mul_hi_u32 s18, s14, s19
	s_mul_i32 s18, s18, s17
	s_sub_i32 s14, s14, s18
	s_sub_i32 s18, s14, s17
	s_cmp_ge_u32 s14, s17
	s_cselect_b32 s14, s18, s14
	s_sub_i32 s18, s14, s17
	s_cmp_ge_u32 s14, s17
	s_cselect_b32 s14, s18, s14
	s_xor_b32 s14, s14, s15
	s_sub_i32 s14, s14, s15
	s_add_i32 s14, s14, s16
	s_ashr_i32 s15, s14, 31
	s_lshl_b64 s[14:15], s[14:15], 14
	v_lshl_add_u64 v[26:27], v[2:3], 0, s[14:15]
	s_waitcnt vmcnt(0)
	flat_load_dwordx4 v[8:11], v[26:27]
	flat_load_dwordx4 v[14:17], v[26:27] offset:16
	flat_load_dwordx4 v[18:21], v[26:27] offset:32
	flat_load_dwordx4 v[22:25], v[26:27] offset:48
	s_waitcnt vmcnt(0) lgkmcnt(0)
	v_mov_b32_e32 v26, v9
	v_mov_b32_e32 v27, v10
	v_mov_b32_e32 v28, v15
	v_mov_b32_e32 v29, v16
	v_mov_b32_e32 v9, v11
	v_mov_b32_e32 v15, v17
	v_mov_b32_e32 v10, v19
	v_mov_b32_e32 v16, v21
	v_pk_add_f32 v[8:9], v[26:27], v[8:9]
	v_pk_add_f32 v[14:15], v[28:29], v[14:15]
	v_pk_add_f32 v[10:11], v[18:19], v[10:11]
	v_pk_add_f32 v[16:17], v[20:21], v[16:17]
	v_pk_add_f32 v[8:9], v[8:9], v[8:9] op_sel:[0,1] op_sel_hi:[1,0]
	v_pk_add_f32 v[14:15], v[14:15], v[14:15] op_sel:[0,1] op_sel_hi:[1,0]
	v_mov_b32_e32 v11, v24
	v_mov_b32_e32 v17, v25
	v_mov_b32_e32 v9, v22
	v_mov_b32_e32 v15, v23
	v_pk_add_f32 v[10:11], v[10:11], v[16:17]
	v_pk_add_f32 v[8:9], v[8:9], v[14:15]
	s_nop 0
	v_pk_add_f32 v[8:9], v[8:9], v[10:11]
	s_nop 0
	v_add_f32_e32 v7, v8, v9
	v_fmamk_f32 v7, v7, 0x3a800000, v6
	v_mul_f32_e32 v8, 0x4b800000, v7
	v_cmp_gt_f32_e32 vcc, s13, v7
	s_nop 1
	v_cndmask_b32_e32 v7, v7, v8, vcc
	v_rsq_f32_e32 v7, v7
	s_nop 0
	v_mul_f32_e32 v8, 0x45800000, v7
	v_cndmask_b32_e32 v7, v7, v8, vcc
	ds_write_b32 v1, v7
	s_branch .LBB0_1552

.LBB0_1712:
	s_cmp_lt_i32 s94, 11
	s_cselect_b64 s[0:1], -1, 0
	s_and_b64 s[2:3], s[0:1], s[2:3]
	s_andn2_b64 vcc, exec, s[2:3]
	s_cbranch_vccnz .LBB0_1739
	v_readlane_b32 s4, v253, 0
	s_mov_b64 s[2:3], s[92:93]
	v_readlane_b32 s5, v253, 1
	s_load_dword s36, s[4:5], 0xf0
	v_and_b32_e32 v0, 0xff, v176
	v_lshlrev_b32_e32 v0, 6, v0
	s_waitcnt lgkmcnt(0)
	v_mov_b32_e32 v1, 0
	s_mov_b64 s[4:5], 0x1f400000
	v_lshlrev_b32_e32 v10, 2, v176
	v_cvt_f32_u32_e32 v2, s36
	s_movk_i32 s6, 0x100
	v_readfirstlane_b32 s33, v176
	v_cmp_gt_u32_e64 s[6:7], s6, v176
	v_rcp_iflag_f32_e32 v2, v2
	s_movk_i32 s12, 0x1c1
	v_mov_b32_e32 v6, 0x358637bd
	s_mov_b32 s13, 0x800000
	v_mul_f32_e32 v2, 0x4f7ffffe, v2
	v_cvt_u32_f32_e32 v4, v2
	v_lshl_add_u64 v[2:3], s[2:3], 0, v[0:1]
	v_lshl_add_u64 v[2:3], v[2:3], 0, s[4:5]
	s_sub_i32 s4, 0, s36
	v_readfirstlane_b32 s5, v4
	s_mul_i32 s4, s4, s5
	s_mul_hi_u32 s4, s5, s4
	s_add_i32 s5, s5, s4
	s_mul_hi_u32 s4, s90, s5
	s_mul_i32 s4, s4, s36
	s_sub_i32 s4, s90, s4
	s_sub_i32 s5, s4, s36
	s_cmp_ge_u32 s4, s36
	s_cselect_b32 s4, s5, s4
	s_sub_i32 s5, s4, s36
	s_cmp_ge_u32 s4, s36
	s_cselect_b32 s4, s5, s4
	s_ashr_i32 s5, s4, 31
	s_ashr_i32 s37, s36, 31
	v_add_u32_e32 v1, 0x20400, v10
	v_mov_b64_e32 v[4:5], 0xdff
	s_mov_b64 s[8:9], s[4:5]
	v_readfirstlane_b32 s10, v176
	s_nop 0
	s_cmpk_lt_u32 s10, 0x100
	s_cbranch_scc1 .Lrstd_skip_4
	s_add_u32 s8, s8, s36
	s_addc_u32 s9, s9, s37

.LBB0_1714:
	s_or_b64 exec, exec, s[10:11]
	s_add_u32 s8, s8, s36
	s_addc_u32 s9, s9, s37
	s_add_u32 s8, s8, s36
	v_add_u32_e32 v1, 0x800, v1
	s_addc_u32 s9, s9, s37
	s_mov_b64 s[10:11], 0

.LBB0_1716:
	v_cmp_gt_i64_e32 vcc, s[8:9], v[4:5]
	s_mov_b64 s[10:11], -1
	s_cbranch_vccnz .LBB0_1715
	s_mov_b64 s[10:11], exec
	s_cbranch_execz .LBB0_1714
	s_ashr_i32 s14, s8, 31
	s_lshr_b32 s14, s14, 29
	s_add_i32 s14, s8, s14
	s_ashr_i32 s15, s14, 3
	s_and_b32 s14, s14, -8
	s_sub_i32 s14, s8, s14
	s_cmp_lt_i32 s14, 0
	s_cselect_b32 s16, s12, 0x1c0
	s_mul_i32 s14, s16, s14
	s_add_i32 s14, s14, s15
	s_mul_hi_i32 s15, s14, 0x92492493
	s_add_i32 s15, s15, s14
	s_lshr_b32 s16, s15, 31
	s_ashr_i32 s15, s15, 7
	s_add_i32 s15, s15, s16
	s_lshl_b32 s16, s15, 3
	s_sub_i32 s17, 0x80, s16
	s_min_i32 s17, s17, 8
	s_abs_i32 s17, s17
	v_cvt_f32_u32_e32 v7, s17
	s_sub_i32 s18, 0, s17
	s_mulk_i32 s15, 0xe0
	s_sub_i32 s14, s14, s15
	v_rcp_iflag_f32_e32 v7, v7
	s_ashr_i32 s15, s14, 31
	s_abs_i32 s14, s14
	v_mul_f32_e32 v7, 0x4f7ffffe, v7
	v_cvt_u32_f32_e32 v7, v7
	s_nop 0
	v_readfirstlane_b32 s19, v7
	s_mul_i32 s18, s18, s19
	s_mul_hi_u32 s18, s19, s18
	s_add_i32 s19, s19, s18
	s_mul_hi_u32 s18, s14, s19
	s_mul_i32 s18, s18, s17
	s_sub_i32 s14, s14, s18
	s_sub_i32 s18, s14, s17
	s_cmp_ge_u32 s14, s17
	s_cselect_b32 s14, s18, s14
	s_sub_i32 s18, s14, s17
	s_cmp_ge_u32 s14, s17
	s_cselect_b32 s14, s18, s14
	s_xor_b32 s14, s14, s15
	s_sub_i32 s14, s14, s15
	s_add_i32 s14, s14, s16
	s_ashr_i32 s15, s14, 31
	s_lshl_b64 s[14:15], s[14:15], 14
	v_lshl_add_u64 v[8:9], v[2:3], 0, s[14:15]
	s_waitcnt vmcnt(0)
	flat_load_dwordx4 v[12:15], v[8:9]
	flat_load_dwordx4 v[16:19], v[8:9] offset:16
	flat_load_dwordx4 v[20:23], v[8:9] offset:32
	flat_load_dwordx4 v[24:27], v[8:9] offset:48
	s_waitcnt vmcnt(0) lgkmcnt(0)
	v_mov_b32_e32 v8, v13
	v_mov_b32_e32 v9, v14
	v_mov_b32_e32 v28, v17
	v_mov_b32_e32 v29, v18
	v_mov_b32_e32 v13, v15
	v_mov_b32_e32 v17, v19
	v_mov_b32_e32 v14, v21
	v_mov_b32_e32 v18, v23
	v_pk_add_f32 v[8:9], v[8:9], v[12:13]
	v_pk_add_f32 v[12:13], v[28:29], v[16:17]
	v_pk_add_f32 v[14:15], v[20:21], v[14:15]
	v_pk_add_f32 v[16:17], v[22:23], v[18:19]
	v_pk_add_f32 v[8:9], v[8:9], v[8:9] op_sel:[0,1] op_sel_hi:[1,0]
	v_pk_add_f32 v[12:13], v[12:13], v[12:13] op_sel:[0,1] op_sel_hi:[1,0]
	v_mov_b32_e32 v15, v26
	v_mov_b32_e32 v17, v27
	v_mov_b32_e32 v9, v24
	v_mov_b32_e32 v13, v25
	v_pk_add_f32 v[14:15], v[14:15], v[16:17]
	v_pk_add_f32 v[8:9], v[8:9], v[12:13]
	s_nop 0
	v_pk_add_f32 v[8:9], v[8:9], v[14:15]
	s_nop 0
	v_add_f32_e32 v7, v8, v9
	v_fmamk_f32 v7, v7, 0x3a800000, v6
	v_mul_f32_e32 v8, 0x4b800000, v7
	v_cmp_gt_f32_e32 vcc, s13, v7
	s_nop 1
	v_cndmask_b32_e32 v7, v7, v8, vcc
	v_rsq_f32_e32 v7, v7
	s_nop 0
	v_mul_f32_e32 v8, 0x45800000, v7
	v_cndmask_b32_e32 v7, v7, v8, vcc
	ds_write_b32 v1, v7
	s_branch .LBB0_1714

.LBB0_2234:
	s_cmp_lt_i32 s94, 16
	s_cselect_b64 s[0:1], -1, 0
	s_and_b64 s[2:3], s[0:1], s[2:3]
	s_andn2_b64 vcc, exec, s[2:3]
	s_cbranch_vccnz .LBB0_2253
	v_readlane_b32 s2, v253, 0
	s_mov_b64 s[8:9], s[92:93]
	v_readlane_b32 s3, v253, 1
	s_load_dword s29, s[2:3], 0xf0
	v_and_b32_e32 v0, 0xff, v176
	v_lshlrev_b32_e32 v0, 6, v0
	s_waitcnt lgkmcnt(0)
	v_mov_b32_e32 v1, 0
	s_mov_b64 s[2:3], 0x1f400000
	v_lshlrev_b32_e32 v12, 2, v176
	v_cvt_f32_u32_e32 v2, s29
	s_movk_i32 s4, 0x100
	v_readfirstlane_b32 s28, v176
	v_cmp_gt_u32_e64 s[6:7], s4, v176
	v_rcp_iflag_f32_e32 v2, v2
	s_movk_i32 s12, 0x161
	v_mov_b32_e32 v6, 0x358637bd
	s_mov_b32 s13, 0x800000
	v_mul_f32_e32 v2, 0x4f7ffffe, v2
	v_cvt_u32_f32_e32 v4, v2
	v_lshl_add_u64 v[2:3], s[8:9], 0, v[0:1]
	v_lshl_add_u64 v[2:3], v[2:3], 0, s[2:3]
	s_sub_i32 s2, 0, s29
	v_readfirstlane_b32 s3, v4
	s_mul_i32 s2, s2, s3
	s_mul_hi_u32 s2, s3, s2
	s_add_i32 s3, s3, s2
	s_mul_hi_u32 s2, s90, s3
	s_mul_i32 s2, s2, s29
	s_sub_i32 s2, s90, s2
	s_sub_i32 s3, s2, s29
	s_cmp_ge_u32 s2, s29
	s_cselect_b32 s2, s3, s2
	s_sub_i32 s3, s2, s29
	s_cmp_ge_u32 s2, s29
	s_cselect_b32 s2, s3, s2
	s_ashr_i32 s3, s2, 31
	s_ashr_i32 s30, s29, 31
	v_add_u32_e32 v1, 0x20400, v12
	v_mov_b64_e32 v[4:5], 0xaff
	s_mov_b64 s[4:5], s[2:3]
	v_readfirstlane_b32 s10, v176
	s_nop 0
	s_cmpk_lt_u32 s10, 0x100
	s_cbranch_scc1 .Lrstd_skip_5
	s_add_u32 s4, s4, s29
	s_addc_u32 s5, s5, s30
